# RWKV-7 state scan: step A's last state-tile matrix op issued before the mid barrier instead of after it, so the step-B conversions do not wait on it
# baseline (speedup 1.0000x reference)
.LBB0_433:
	s_mul_i32 s1, s0, 37
	s_bfe_u32 s2, s1, 0x80008
	s_lshr_b32 s1, s1, 8
	s_sub_i32 s1, s0, s1
	s_bfe_u32 s1, s1, 0x70001
	s_add_i32 s1, s1, s2
	s_bfe_u32 s1, s1, 0x60002
	s_mul_i32 s1, s1, 7
	s_sub_i32 s1, s0, s1
	s_and_b32 s1, s1, 0xff
	s_mulk_i32 s1, 0x4800
	v_add_u32_e32 v136, s1, v151
	ds_read_b128 v[228:231], v136 offset:17792
	ds_read_b128 v[232:235], v136 offset:17824
	ds_read_b128 v[236:239], v136 offset:17856
	ds_read_b128 v[240:243], v136 offset:17888
	ds_read_b128 v[128:131], v136 offset:17920
	ds_read_b128 v[132:135], v136 offset:17952
	ds_read_b128 v[220:223], v136 offset:17984
	ds_read_b128 v[224:227], v136 offset:18016
	v_cvt_pk_bf16_f32 v112, v16, v17
	v_cvt_pk_bf16_f32 v113, v18, v19
	v_cvt_pk_bf16_f32 v114, v20, v21
	v_cvt_pk_bf16_f32 v115, v22, v23
	v_cvt_pk_bf16_f32 v116, v24, v25
	v_cvt_pk_bf16_f32 v117, v26, v27
	v_cvt_pk_bf16_f32 v118, v28, v29
	v_cvt_pk_bf16_f32 v119, v30, v31
	s_nop 1
	v_mfma_f32_32x32x16_bf16 v[32:47], v[48:51], v[112:115], 0
	v_mfma_f32_32x32x16_bf16 v[32:47], v[52:55], v[116:119], v[32:47]
	v_cvt_pk_bf16_f32 v120, v0, v1
	v_cvt_pk_bf16_f32 v121, v2, v3
	v_cvt_pk_bf16_f32 v122, v4, v5
	v_cvt_pk_bf16_f32 v123, v6, v7
	v_cvt_pk_bf16_f32 v124, v8, v9
	v_cvt_pk_bf16_f32 v125, v10, v11
	v_cvt_pk_bf16_f32 v126, v12, v13
	v_cvt_pk_bf16_f32 v127, v14, v15
	s_waitcnt lgkmcnt(0)
	v_pk_mul_f32 v[16:17], v[16:17], v[228:229]
	v_pk_mul_f32 v[18:19], v[18:19], v[230:231]
	v_pk_mul_f32 v[20:21], v[20:21], v[232:233]
	v_pk_mul_f32 v[22:23], v[22:23], v[234:235]
	v_pk_mul_f32 v[24:25], v[24:25], v[236:237]
	v_pk_mul_f32 v[26:27], v[26:27], v[238:239]
	v_pk_mul_f32 v[28:29], v[28:29], v[240:241]
	v_pk_mul_f32 v[30:31], v[30:31], v[242:243]
	v_mul_f32_e64 v0, v0, v128
	v_mul_f32_e64 v1, v1, v129
	v_mul_f32_e64 v2, v2, v130
	v_mul_f32_e64 v3, v3, v131
	v_mul_f32_e64 v4, v4, v132
	v_mul_f32_e64 v5, v5, v133
	v_pk_mul_f32 v[6:7], v[6:7], v[134:135]
	s_or_b32 s1, s0, 1
	v_mfma_f32_32x32x16_bf16 v[16:31], v[72:75], v[112:115], v[16:31]
	s_and_b32 s2, s1, 0xff
	v_mul_f32_e64 v8, v8, v220
	v_mul_f32_e64 v9, v9, v221
	v_mul_f32_e64 v10, v10, v222
	v_mul_f32_e64 v11, v11, v223
	v_pk_mul_f32 v[12:13], v[12:13], v[224:225]
	v_pk_mul_f32 v[14:15], v[14:15], v[226:227]
	s_mul_i32 s2, s2, 37
	s_lshr_b32 s2, s2, 8
	s_sub_i32 s3, s1, s2
	s_bfe_u32 s3, s3, 0x70001
	s_add_i32 s3, s3, s2
	s_lshr_b32 s2, s3, 2
	s_mul_i32 s2, s2, 7
	s_sub_i32 s1, s1, s2
	s_and_b32 s1, s1, 0xff
	v_mfma_f32_32x32x16_bf16 v[0:15], v[88:91], v[112:115], v[0:15]
	s_mulk_i32 s1, 0x4800
	s_add_i32 s1, s1, 0
	v_add_u32_e32 v192, s1, v144
	v_add_u32_e32 v180, v192, v156
	s_cmpk_gt_u32 s0, 0x7d
	s_cselect_b64 s[2:3], -1, 0
	v_mfma_f32_32x32x16_bf16 v[16:31], v[76:79], v[116:119], v[16:31]
	s_and_b64 vcc, exec, s[2:3]
	v_mfma_f32_32x32x16_bf16 v[32:47], v[56:59], v[120:123], v[32:47]
	v_mfma_f32_32x32x16_bf16 v[0:15], v[92:95], v[116:119], v[0:15]
	v_mfma_f32_32x32x16_bf16 v[16:31], v[80:83], v[120:123], v[16:31]
	v_mfma_f32_32x32x16_bf16 v[32:47], v[60:63], v[124:127], v[32:47]
	v_mfma_f32_32x32x16_bf16 v[0:15], v[96:99], v[120:123], v[0:15]
	v_mfma_f32_32x32x16_bf16 v[16:31], v[84:87], v[124:127], v[16:31]
	v_mfma_f32_32x32x16_bf16 v[32:47], v[68:71], v[64:67], v[32:47]
	v_mfma_f32_32x32x16_bf16 v[0:15], v[100:103], v[124:127], v[0:15]
	s_nop 10
	v_add_u32_e32 v45, s1, v153
	v_add_u32_e32 v46, v45, v152
	v_add_u32_e32 v160, v45, v155
	v_add_u32_e32 v44, v192, v150
	ds_read2_b64 v[40:43], v46 offset1:2
	ds_read2_b64 v[116:119], v46 offset0:4 offset1:6
	ds_read2_b64 v[120:123], v46 offset0:8 offset1:10
	ds_read2_b64 v[124:127], v46 offset0:12 offset1:14
	v_add_u32_e32 v46, v192, v154
	v_add_u32_e32 v132, 0x800, v160
	v_mfma_f32_32x32x16_bf16 v[16:31], v[104:107], v[64:67], v[16:31]
	v_mfma_f32_32x32x16_bf16 v[0:15], v[108:111], v[64:67], v[0:15]
	v_add_u32_e32 v172, 0x1800, v160
	ds_read_b128 v[112:115], v44 offset:14720
	ds_read_b128 v[128:131], v46 offset:2176
	ds_read2_b64 v[44:47], v132 offset0:112 offset1:114
	ds_read2_b64 v[140:143], v132 offset0:116 offset1:118
	ds_read2_b64 v[136:139], v132 offset0:120 offset1:122
	ds_read2_b64 v[132:135], v132 offset0:124 offset1:126
	ds_read2_b64 v[160:163], v172 offset0:144 offset1:146
	ds_read2_b64 v[164:167], v172 offset0:148 offset1:150
	ds_read2_b64 v[168:171], v172 offset0:152 offset1:154
	ds_read2_b64 v[172:175], v172 offset0:156 offset1:158
	ds_read_b128 v[176:179], v180 offset:11648
	ds_read_b128 v[180:183], v180 offset:13184
	ds_read_b128 v[220:223], v192 offset:17888
	ds_read_b128 v[224:227], v192 offset:17856
	ds_read_b128 v[228:231], v192 offset:17824
	ds_read_b128 v[232:235], v192 offset:17792
	ds_read_b128 v[236:239], v192 offset:18016
	ds_read_b128 v[240:243], v192 offset:17984
	ds_read_b128 v[244:247], v192 offset:17952
	ds_write2st64_b32 v158, v32, v33 offset1:1
	ds_write2st64_b32 v158, v34, v35 offset0:2 offset1:3
	ds_write2st64_b32 v158, v36, v37 offset0:8 offset1:9
	ds_write2st64_b32 v158, v38, v39 offset0:10 offset1:11
	s_waitcnt lgkmcnt(0)
	s_barrier
	ds_read_b128 v[36:39], v192 offset:17920
	v_cvt_pk_bf16_f32 v32, v16, v17
	v_cvt_pk_bf16_f32 v33, v18, v19
	v_cvt_pk_bf16_f32 v34, v20, v21
	v_cvt_pk_bf16_f32 v35, v22, v23
	v_cvt_pk_bf16_f32 v184, v24, v25
	v_cvt_pk_bf16_f32 v185, v26, v27
	v_cvt_pk_bf16_f32 v186, v28, v29
	v_cvt_pk_bf16_f32 v187, v30, v31
	v_cvt_pk_bf16_f32 v188, v0, v1
	v_cvt_pk_bf16_f32 v189, v2, v3
	v_cvt_pk_bf16_f32 v190, v4, v5
	v_cvt_pk_bf16_f32 v191, v6, v7
	v_cvt_pk_bf16_f32 v216, v8, v9
	v_cvt_pk_bf16_f32 v217, v10, v11
	v_cvt_pk_bf16_f32 v218, v12, v13
	v_cvt_pk_bf16_f32 v219, v14, v15
	v_pk_mul_f32 v[28:29], v[28:29], v[220:221]
	v_pk_mul_f32 v[30:31], v[30:31], v[222:223]
	v_pk_mul_f32 v[24:25], v[24:25], v[224:225]
	v_pk_mul_f32 v[26:27], v[26:27], v[226:227]
	v_pk_mul_f32 v[20:21], v[20:21], v[228:229]
	v_pk_mul_f32 v[22:23], v[22:23], v[230:231]
	v_pk_mul_f32 v[18:19], v[18:19], v[234:235]
	v_pk_mul_f32 v[16:17], v[16:17], v[232:233]
	v_pk_mul_f32 v[12:13], v[12:13], v[236:237]
	v_pk_mul_f32 v[14:15], v[14:15], v[238:239]
	v_mfma_f32_32x32x16_bf16 v[16:31], v[44:47], v[32:35], v[16:31]
	v_mul_f32_e64 v8, v8, v240
	v_mul_f32_e64 v9, v9, v241
	v_mul_f32_e64 v10, v10, v242
	v_mul_f32_e64 v11, v11, v243
	v_pk_mul_f32 v[4:5], v[4:5], v[244:245]
	v_pk_mul_f32 v[6:7], v[6:7], v[246:247]
	v_mfma_f32_32x32x16_bf16 v[16:31], v[140:143], v[184:187], v[16:31]
	s_waitcnt lgkmcnt(0)
	v_mul_f32_e64 v2, v2, v38
	v_mul_f32_e64 v3, v3, v39
	v_mul_f32_e64 v0, v0, v36
	v_mul_f32_e64 v1, v1, v37
	s_nop 1
	v_mfma_f32_32x32x16_bf16 v[0:15], v[160:163], v[32:35], v[0:15]
	v_mfma_f32_32x32x16_bf16 v[32:47], v[40:43], v[32:35], 0
	v_mfma_f32_32x32x16_bf16 v[32:47], v[116:119], v[184:187], v[32:47]
	v_mfma_f32_32x32x16_bf16 v[0:15], v[164:167], v[184:187], v[0:15]
	v_mfma_f32_32x32x16_bf16 v[32:47], v[120:123], v[188:191], v[32:47]
	v_mfma_f32_32x32x16_bf16 v[16:31], v[136:139], v[188:191], v[16:31]
	v_mfma_f32_32x32x16_bf16 v[0:15], v[168:171], v[188:191], v[0:15]
	v_mfma_f32_32x32x16_bf16 v[32:47], v[124:127], v[216:219], v[32:47]
	v_mfma_f32_32x32x16_bf16 v[16:31], v[132:135], v[216:219], v[16:31]
	v_mfma_f32_32x32x16_bf16 v[0:15], v[172:175], v[216:219], v[0:15]
	v_mfma_f32_32x32x16_bf16 v[32:47], v[128:131], v[112:115], v[32:47]
	v_mfma_f32_32x32x16_bf16 v[16:31], v[176:179], v[112:115], v[16:31]
	v_mfma_f32_32x32x16_bf16 v[0:15], v[180:183], v[112:115], v[0:15]
	s_cbranch_vccnz .LBB0_432
	s_add_i32 s1, s0, 2
	s_and_b32 s4, s1, 0xff
	s_mul_i32 s4, s4, 37
	s_lshr_b32 s5, s4, 8
	s_sub_i32 s5, s1, s5
	s_bfe_u32 s5, s5, 0x70001
	s_bfe_u32 s4, s4, 0x80008
	s_add_i32 s5, s5, s4
	s_bfe_u32 s4, s5, 0x60002
	s_mul_i32 s4, s4, 7
	s_sub_i32 s1, s1, s4
	s_and_b32 s1, s1, 0xff
	s_mulk_i32 s1, 0x4800
	s_add_i32 s1, s1, 0
	v_add_u32_e32 v40, s1, v144
	v_add_u32_e32 v42, s1, v153
	v_add_u32_e32 v41, v40, v150
	v_add_u32_e32 v43, v42, v152
	ds_read2_b64 v[48:51], v43 offset1:2
	ds_read2_b64 v[52:55], v43 offset0:4 offset1:6
	ds_read2_b64 v[56:59], v43 offset0:8 offset1:10
	ds_read2_b64 v[60:63], v43 offset0:12 offset1:14
	v_add_u32_e32 v43, v40, v154
	ds_read_b128 v[64:67], v41 offset:14720
	ds_read_b128 v[68:71], v43 offset:2176
	v_add_u32_e32 v41, v42, v155
	v_add_u32_e32 v42, 0x800, v41
	v_add_u32_e32 v41, 0x1800, v41
	ds_read2_b64 v[72:75], v42 offset0:112 offset1:114
	ds_read2_b64 v[76:79], v42 offset0:116 offset1:118
	ds_read2_b64 v[80:83], v42 offset0:120 offset1:122
	ds_read2_b64 v[84:87], v42 offset0:124 offset1:126
	v_add_u32_e32 v40, v40, v156
	ds_read2_b64 v[88:91], v41 offset0:144 offset1:146
	ds_read2_b64 v[92:95], v41 offset0:148 offset1:150
	ds_read2_b64 v[96:99], v41 offset0:152 offset1:154
	ds_read2_b64 v[100:103], v41 offset0:156 offset1:158
	ds_read_b128 v[104:107], v40 offset:11648
	ds_read_b128 v[108:111], v40 offset:13184
	s_branch .LBB0_432
